# prologue modulation GEMM: global loads + counted vmcnt(32) waits so the two weight batches really overlap the MFMAs
# speedup vs baseline: 1.0341x; 1.0029x over previous
; #define LAS __attribute__((address_space(3)))
; #define MOD_LOAD(W) do { _Pragma("unroll") for (int kk = 0; kk < 32; ++kk) { W[kk] = *wp; wp += 2 * NMOD; asm volatile("" : "+v"(wp)); } } while (0)
; #define MOD_MMA(W, KP0) do { _Pragma("unroll") for (int kk = 0; kk < 32; ++kk) acc = __builtin_amdgcn_mfma_f32_32x32x2f32(ap[((KP0) + kk) * 64], W[kk], acc, 0, 0, 0); } while (0)
; __device__ __forceinline__ void p0_prologue(Frame& F) {
;     ...
;         const int rt = blk / 48, sgp = blk % 48, r32 = lane & 31, hi = lane >> 5;
;         LAS float* SC = (LAS float*)(F.lds + RING_OFF);
;         for (int i = tid; i < 32768; i += NWAVES * 64) { const int j = i >> 10, k = i & 1023; int R = rt * 32 + j; R = R < 144 ? R : 143;
;             const float c = R < NBATCH ? c_prompt[R * DM + k] : c_sample[(R - NBATCH) * DM + k]; SC[k * 32 + j] = c / (1.f + expf(-c)); }
;         __syncthreads();
;         const int s = F.wave & 3, kh = F.wave >> 2, col = (sgp * 4 + s) * 32 + r32;
;         f32x16 acc;
; #pragma unroll
;         for (int r = 0; r < 16; ++r) acc[r] = 0.f;
;         const float* wp = w_mod + (size_t)(kh * 512 + hi) * NMOD + col;
;         const LAS float* ap = SC + (kh * 512 + hi) * 32 + r32;
;     ...
;         float wA[32], wB[32];
;         MOD_LOAD(wA);
; #pragma unroll 1
;         for (int kp = 0; kp < 256; kp += 64) {
;             MOD_LOAD(wB);
;             MOD_MMA(wA, kp);
;             if (kp + 64 >= 256) wp -= 64 * NMOD;
;             MOD_LOAD(wA);
;             MOD_MMA(wB, kp + 32);
.LBB0_30:
	s_or_b64 exec, exec, s[36:37]
	s_mul_i32 s4, s3, 48
	s_sub_i32 s4, s81, s4
	s_bfe_u32 s6, s76, 0x20006
	s_lshl_b32 s4, s4, 7
	s_lshl_b32 s5, s6, 5
	v_and_b32_e32 v4, 31, v1
	v_ashrrev_i32_e32 v19, 5, v1
	s_or_b32 s4, s4, s5
	s_lshr_b32 s7, s76, 8
	v_or_b32_e32 v20, s4, v4
	v_lshl_add_u32 v5, s7, 9, v19
	s_movk_i32 s4, 0x6000
	s_waitcnt lgkmcnt(0)
	v_mov_b64_e32 v[2:3], s[34:35]
	v_mad_i64_i32 v[2:3], s[4:5], v5, s4, v[2:3]
	v_ashrrev_i32_e32 v21, 31, v20
	v_lshl_add_u64 v[2:3], v[20:21], 2, v[2:3]
	s_mov_b64 s[4:5], 0xc000
	s_barrier
	global_load_dword v24, v[2:3], off
	v_lshl_add_u64 v[2:3], v[2:3], 0, s[4:5]
	global_load_dword v25, v[2:3], off
	v_lshl_add_u64 v[2:3], v[2:3], 0, s[4:5]
	global_load_dword v26, v[2:3], off
	v_lshl_add_u64 v[2:3], v[2:3], 0, s[4:5]
	global_load_dword v27, v[2:3], off
	v_lshl_add_u64 v[2:3], v[2:3], 0, s[4:5]
	global_load_dword v29, v[2:3], off
	v_lshl_add_u64 v[2:3], v[2:3], 0, s[4:5]
	global_load_dword v31, v[2:3], off
	v_lshl_add_u64 v[2:3], v[2:3], 0, s[4:5]
	global_load_dword v33, v[2:3], off
	v_lshl_add_u64 v[2:3], v[2:3], 0, s[4:5]
	global_load_dword v35, v[2:3], off
	v_lshl_add_u64 v[2:3], v[2:3], 0, s[4:5]
	global_load_dword v32, v[2:3], off
	v_lshl_add_u64 v[2:3], v[2:3], 0, s[4:5]
	global_load_dword v36, v[2:3], off
	v_lshl_add_u64 v[2:3], v[2:3], 0, s[4:5]
	global_load_dword v37, v[2:3], off
	v_lshl_add_u64 v[2:3], v[2:3], 0, s[4:5]
	global_load_dword v39, v[2:3], off
	v_lshl_add_u64 v[2:3], v[2:3], 0, s[4:5]
	global_load_dword v40, v[2:3], off
	v_lshl_add_u64 v[2:3], v[2:3], 0, s[4:5]
	global_load_dword v42, v[2:3], off
	v_lshl_add_u64 v[2:3], v[2:3], 0, s[4:5]
	global_load_dword v43, v[2:3], off
	v_lshl_add_u64 v[2:3], v[2:3], 0, s[4:5]
	global_load_dword v46, v[2:3], off
	v_lshl_add_u64 v[2:3], v[2:3], 0, s[4:5]
	global_load_dword v44, v[2:3], off
	v_lshl_add_u64 v[2:3], v[2:3], 0, s[4:5]
	global_load_dword v47, v[2:3], off
	v_lshl_add_u64 v[2:3], v[2:3], 0, s[4:5]
	global_load_dword v48, v[2:3], off
	v_lshl_add_u64 v[2:3], v[2:3], 0, s[4:5]
	global_load_dword v50, v[2:3], off
	v_lshl_add_u64 v[2:3], v[2:3], 0, s[4:5]
	global_load_dword v51, v[2:3], off
	v_lshl_add_u64 v[2:3], v[2:3], 0, s[4:5]
	global_load_dword v53, v[2:3], off
	v_lshl_add_u64 v[2:3], v[2:3], 0, s[4:5]
	global_load_dword v55, v[2:3], off
	v_lshl_add_u64 v[2:3], v[2:3], 0, s[4:5]
	global_load_dword v56, v[2:3], off
	v_lshl_add_u64 v[2:3], v[2:3], 0, s[4:5]
	global_load_dword v54, v[2:3], off
	v_lshl_add_u64 v[2:3], v[2:3], 0, s[4:5]
	global_load_dword v52, v[2:3], off
	v_lshl_add_u64 v[2:3], v[2:3], 0, s[4:5]
	global_load_dword v49, v[2:3], off
	v_lshl_add_u64 v[2:3], v[2:3], 0, s[4:5]
	global_load_dword v45, v[2:3], off
	v_lshl_add_u64 v[2:3], v[2:3], 0, s[4:5]
	global_load_dword v41, v[2:3], off
	v_lshl_add_u64 v[2:3], v[2:3], 0, s[4:5]
	global_load_dword v38, v[2:3], off
	v_lshl_add_u64 v[2:3], v[2:3], 0, s[4:5]
	global_load_dword v34, v[2:3], off
	v_lshl_add_u64 v[2:3], v[2:3], 0, s[4:5]
	global_load_dword v30, v[2:3], off
	v_lshlrev_b32_e32 v5, 7, v5
	v_lshl_add_u64 v[22:23], v[2:3], 0, s[4:5]
	v_lshlrev_b32_e32 v2, 2, v4
	v_add3_u32 v28, 0, v5, v2
	v_mov_b32_e32 v2, 0
	s_movk_i32 s8, 0xffc0
	v_mov_b32_e32 v3, v2
	v_mov_b32_e32 v4, v2
	v_mov_b32_e32 v5, v2
	v_mov_b32_e32 v6, v2
	v_mov_b32_e32 v7, v2
	v_mov_b32_e32 v8, v2
	v_mov_b32_e32 v9, v2
	v_mov_b32_e32 v10, v2
	v_mov_b32_e32 v11, v2
	v_mov_b32_e32 v12, v2
	v_mov_b32_e32 v13, v2
	v_mov_b32_e32 v14, v2
	v_mov_b32_e32 v15, v2
	v_mov_b32_e32 v16, v2
	v_mov_b32_e32 v17, v2
.LBB0_31:
	global_load_dword v66, v[22:23], off
	v_lshl_add_u64 v[22:23], v[22:23], 0, s[4:5]
	global_load_dword v67, v[22:23], off
	v_lshl_add_u64 v[22:23], v[22:23], 0, s[4:5]
	global_load_dword v68, v[22:23], off
	v_lshl_add_u64 v[22:23], v[22:23], 0, s[4:5]
	global_load_dword v69, v[22:23], off
	v_lshl_add_u64 v[22:23], v[22:23], 0, s[4:5]
	global_load_dword v70, v[22:23], off
	v_lshl_add_u64 v[22:23], v[22:23], 0, s[4:5]
	global_load_dword v71, v[22:23], off
	v_lshl_add_u64 v[22:23], v[22:23], 0, s[4:5]
	global_load_dword v72, v[22:23], off
	v_lshl_add_u64 v[22:23], v[22:23], 0, s[4:5]
	global_load_dword v73, v[22:23], off
	v_lshl_add_u64 v[22:23], v[22:23], 0, s[4:5]
	global_load_dword v74, v[22:23], off
	v_lshl_add_u64 v[22:23], v[22:23], 0, s[4:5]
	global_load_dword v75, v[22:23], off
	v_lshl_add_u64 v[22:23], v[22:23], 0, s[4:5]
	global_load_dword v76, v[22:23], off
	v_lshl_add_u64 v[22:23], v[22:23], 0, s[4:5]
	global_load_dword v77, v[22:23], off
	v_lshl_add_u64 v[22:23], v[22:23], 0, s[4:5]
	global_load_dword v78, v[22:23], off
	v_lshl_add_u64 v[22:23], v[22:23], 0, s[4:5]
	global_load_dword v79, v[22:23], off
	v_lshl_add_u64 v[22:23], v[22:23], 0, s[4:5]
	global_load_dword v80, v[22:23], off
	v_lshl_add_u64 v[22:23], v[22:23], 0, s[4:5]
	global_load_dword v81, v[22:23], off
	v_lshl_add_u64 v[22:23], v[22:23], 0, s[4:5]
	global_load_dword v82, v[22:23], off
	v_lshl_add_u64 v[22:23], v[22:23], 0, s[4:5]
	global_load_dword v83, v[22:23], off
	v_lshl_add_u64 v[22:23], v[22:23], 0, s[4:5]
	global_load_dword v84, v[22:23], off
	v_lshl_add_u64 v[22:23], v[22:23], 0, s[4:5]
	global_load_dword v85, v[22:23], off
	v_lshl_add_u64 v[22:23], v[22:23], 0, s[4:5]
	global_load_dword v86, v[22:23], off
	v_lshl_add_u64 v[22:23], v[22:23], 0, s[4:5]
	global_load_dword v87, v[22:23], off
	v_lshl_add_u64 v[22:23], v[22:23], 0, s[4:5]
	global_load_dword v88, v[22:23], off
	v_lshl_add_u64 v[22:23], v[22:23], 0, s[4:5]
	global_load_dword v89, v[22:23], off
	v_lshl_add_u64 v[22:23], v[22:23], 0, s[4:5]
	global_load_dword v90, v[22:23], off
	v_lshl_add_u64 v[22:23], v[22:23], 0, s[4:5]
	global_load_dword v91, v[22:23], off
	v_lshl_add_u64 v[22:23], v[22:23], 0, s[4:5]
	global_load_dword v92, v[22:23], off
	v_lshl_add_u64 v[22:23], v[22:23], 0, s[4:5]
	global_load_dword v93, v[22:23], off
	v_lshl_add_u64 v[22:23], v[22:23], 0, s[4:5]
	global_load_dword v94, v[22:23], off
	v_lshl_add_u64 v[22:23], v[22:23], 0, s[4:5]
	global_load_dword v95, v[22:23], off
	v_lshl_add_u64 v[22:23], v[22:23], 0, s[4:5]
	global_load_dword v96, v[22:23], off
	v_lshl_add_u64 v[22:23], v[22:23], 0, s[4:5]
	global_load_dword v97, v[22:23], off
	v_lshl_add_u64 v[22:23], v[22:23], 0, s[4:5]
	ds_read2st64_b32 v[58:59], v28 offset1:1
	ds_read2st64_b32 v[60:61], v28 offset0:2 offset1:3
	ds_read2st64_b32 v[62:63], v28 offset0:4 offset1:5
	ds_read2st64_b32 v[64:65], v28 offset0:6 offset1:7
	s_waitcnt vmcnt(32) lgkmcnt(0)
; #define MOD_LOAD(W) do { _Pragma("unroll") for (int kk = 0; kk < 32; ++kk) { W[kk] = *wp; wp += 2 * NMOD; asm volatile("" : "+v"(wp)); } } while (0)
; #define MOD_MMA(W, KP0) do { _Pragma("unroll") for (int kk = 0; kk < 32; ++kk) acc = __builtin_amdgcn_mfma_f32_32x32x2f32(ap[((KP0) + kk) * 64], W[kk], acc, 0, 0, 0); } while (0)
; __device__ __forceinline__ void p0_prologue(Frame& F) {
;     ...
;         float wA[32], wB[32];
;         MOD_LOAD(wA);
; #pragma unroll 1
;         for (int kp = 0; kp < 256; kp += 64) {
;             MOD_LOAD(wB);
;             MOD_MMA(wA, kp);
;             if (kp + 64 >= 256) wp -= 64 * NMOD;
;             MOD_LOAD(wA);
;             MOD_MMA(wB, kp + 32);
;         }
	v_mfma_f32_32x32x2_f32 v[2:17], v58, v24, v[2:17]
	s_add_i32 s8, s8, 64
	s_cmpk_gt_u32 s8, 0xbf
	s_cselect_b32 s25, -1, 0
	s_cselect_b32 s24, 0xffe80000, 0
	v_lshl_add_u64 v[22:23], v[22:23], 0, s[24:25]
	s_cmpk_lt_u32 s8, 0xc0
	v_mfma_f32_32x32x2_f32 v[2:17], v59, v25, v[2:17]
	v_mfma_f32_32x32x2_f32 v[2:17], v60, v26, v[2:17]
	v_mfma_f32_32x32x2_f32 v[2:17], v61, v27, v[2:17]
	ds_read2st64_b32 v[24:25], v28 offset0:8 offset1:9
	ds_read2st64_b32 v[26:27], v28 offset0:10 offset1:11
	ds_read2st64_b32 v[58:59], v28 offset0:12 offset1:13
	ds_read2st64_b32 v[60:61], v28 offset0:14 offset1:15
	v_mfma_f32_32x32x2_f32 v[2:17], v62, v29, v[2:17]
	v_mfma_f32_32x32x2_f32 v[2:17], v63, v31, v[2:17]
	v_mfma_f32_32x32x2_f32 v[2:17], v64, v33, v[2:17]
	v_mfma_f32_32x32x2_f32 v[2:17], v65, v35, v[2:17]
	s_waitcnt lgkmcnt(3)
	v_mfma_f32_32x32x2_f32 v[2:17], v24, v32, v[2:17]
	v_mfma_f32_32x32x2_f32 v[2:17], v25, v36, v[2:17]
	s_waitcnt lgkmcnt(2)
	v_mfma_f32_32x32x2_f32 v[2:17], v26, v37, v[2:17]
	v_mfma_f32_32x32x2_f32 v[2:17], v27, v39, v[2:17]
	ds_read2st64_b32 v[24:25], v28 offset0:16 offset1:17
	ds_read2st64_b32 v[26:27], v28 offset0:18 offset1:19
	ds_read2st64_b32 v[32:33], v28 offset0:20 offset1:21
	ds_read2st64_b32 v[36:37], v28 offset0:22 offset1:23
	s_waitcnt lgkmcnt(5)
	v_mfma_f32_32x32x2_f32 v[2:17], v58, v40, v[2:17]
	v_mfma_f32_32x32x2_f32 v[2:17], v59, v42, v[2:17]
	s_waitcnt lgkmcnt(4)
	v_mfma_f32_32x32x2_f32 v[2:17], v60, v43, v[2:17]
	v_mfma_f32_32x32x2_f32 v[2:17], v61, v46, v[2:17]
	s_waitcnt lgkmcnt(3)
	v_mfma_f32_32x32x2_f32 v[2:17], v24, v44, v[2:17]
	v_mfma_f32_32x32x2_f32 v[2:17], v25, v47, v[2:17]
	s_waitcnt lgkmcnt(2)
	v_mfma_f32_32x32x2_f32 v[2:17], v26, v48, v[2:17]
	v_mfma_f32_32x32x2_f32 v[2:17], v27, v50, v[2:17]
	v_lshl_add_u64 v[26:27], v[22:23], 0, s[4:5]
	s_waitcnt lgkmcnt(1)
	v_mfma_f32_32x32x2_f32 v[2:17], v32, v51, v[2:17]
	v_mfma_f32_32x32x2_f32 v[2:17], v33, v53, v[2:17]
	s_waitcnt lgkmcnt(0)
	v_mfma_f32_32x32x2_f32 v[2:17], v36, v55, v[2:17]
	v_mfma_f32_32x32x2_f32 v[2:17], v37, v56, v[2:17]
	ds_read2st64_b32 v[24:25], v28 offset0:24 offset1:25
	ds_read2st64_b32 v[36:37], v28 offset0:26 offset1:27
	ds_read2st64_b32 v[50:51], v28 offset0:28 offset1:29
	ds_read2st64_b32 v[58:59], v28 offset0:30 offset1:31
	s_waitcnt lgkmcnt(3)
	v_mfma_f32_32x32x2_f32 v[2:17], v24, v54, v[2:17]
	global_load_dword v24, v[22:23], off
	s_nop 0
	v_lshl_add_u64 v[22:23], v[26:27], 0, s[4:5]
	v_mfma_f32_32x32x2_f32 v[2:17], v25, v52, v[2:17]
	global_load_dword v25, v[26:27], off
	global_load_dword v26, v[22:23], off
	v_lshl_add_u64 v[32:33], v[22:23], 0, s[4:5]
	global_load_dword v27, v[32:33], off
	v_lshl_add_u64 v[22:23], v[32:33], 0, s[4:5]
	global_load_dword v29, v[22:23], off
	v_lshl_add_u64 v[32:33], v[22:23], 0, s[4:5]
	global_load_dword v31, v[32:33], off
	v_lshl_add_u64 v[22:23], v[32:33], 0, s[4:5]
	global_load_dword v33, v[22:23], off
	s_waitcnt lgkmcnt(0)
	v_mfma_f32_32x32x2_f32 v[2:17], v36, v49, v[2:17]
	v_lshl_add_u64 v[42:43], v[22:23], 0, s[4:5]
	global_load_dword v35, v[42:43], off
	v_lshl_add_u64 v[22:23], v[42:43], 0, s[4:5]
	global_load_dword v32, v[22:23], off
	v_lshl_add_u64 v[42:43], v[22:23], 0, s[4:5]
	global_load_dword v36, v[42:43], off
	v_lshl_add_u64 v[22:23], v[42:43], 0, s[4:5]
	s_nop 0
	v_lshl_add_u64 v[42:43], v[22:23], 0, s[4:5]
	v_mfma_f32_32x32x2_f32 v[2:17], v37, v45, v[2:17]
	global_load_dword v37, v[22:23], off
	global_load_dword v39, v[42:43], off
	v_lshl_add_u64 v[22:23], v[42:43], 0, s[4:5]
	global_load_dword v40, v[22:23], off
	v_lshl_add_u64 v[42:43], v[22:23], 0, s[4:5]
	s_nop 0
	v_lshl_add_u64 v[22:23], v[42:43], 0, s[4:5]
	global_load_dword v42, v[42:43], off
	global_load_dword v43, v[22:23], off
	v_lshl_add_u64 v[44:45], v[22:23], 0, s[4:5]
	v_mfma_f32_32x32x2_f32 v[2:17], v50, v41, v[2:17]
	v_lshl_add_u64 v[22:23], v[44:45], 0, s[4:5]
	global_load_dword v46, v[44:45], off
	global_load_dword v44, v[22:23], off
	v_lshl_add_u64 v[48:49], v[22:23], 0, s[4:5]
	global_load_dword v47, v[48:49], off
	v_lshl_add_u64 v[22:23], v[48:49], 0, s[4:5]
	global_load_dword v48, v[22:23], off
	v_lshl_add_u64 v[52:53], v[22:23], 0, s[4:5]
	global_load_dword v50, v[52:53], off
	v_lshl_add_u64 v[22:23], v[52:53], 0, s[4:5]
	v_mfma_f32_32x32x2_f32 v[2:17], v51, v38, v[2:17]
	v_lshl_add_u64 v[52:53], v[22:23], 0, s[4:5]
	global_load_dword v51, v[22:23], off
	s_nop 0
	v_lshl_add_u64 v[22:23], v[52:53], 0, s[4:5]
	global_load_dword v53, v[52:53], off
	global_load_dword v55, v[22:23], off
	v_lshl_add_u64 v[56:57], v[22:23], 0, s[4:5]
	s_nop 0
	v_lshl_add_u64 v[22:23], v[56:57], 0, s[4:5]
	global_load_dword v56, v[56:57], off
	global_load_dword v54, v[22:23], off
	v_mfma_f32_32x32x2_f32 v[2:17], v58, v34, v[2:17]
	v_lshl_add_u64 v[60:61], v[22:23], 0, s[4:5]
	global_load_dword v52, v[60:61], off
	v_lshl_add_u64 v[22:23], v[60:61], 0, s[4:5]
	global_load_dword v49, v[22:23], off
	v_lshl_add_u64 v[60:61], v[22:23], 0, s[4:5]
	global_load_dword v45, v[60:61], off
	v_lshl_add_u64 v[22:23], v[60:61], 0, s[4:5]
	global_load_dword v41, v[22:23], off
	v_lshl_add_u64 v[60:61], v[22:23], 0, s[4:5]
	global_load_dword v38, v[60:61], off
	v_mfma_f32_32x32x2_f32 v[2:17], v59, v30, v[2:17]
	v_lshl_add_u64 v[22:23], v[60:61], 0, s[4:5]
	global_load_dword v34, v[22:23], off
	v_lshl_add_u64 v[58:59], v[22:23], 0, s[4:5]
	global_load_dword v30, v[58:59], off
	v_lshl_add_u64 v[22:23], v[58:59], 0, s[4:5]
	ds_read2st64_b32 v[58:59], v28 offset0:32 offset1:33
	ds_read2st64_b32 v[60:61], v28 offset0:34 offset1:35
	ds_read2st64_b32 v[62:63], v28 offset0:36 offset1:37
	ds_read2st64_b32 v[64:65], v28 offset0:38 offset1:39
	s_waitcnt vmcnt(32) lgkmcnt(0)
; #define LAS __attribute__((address_space(3)))
; #define MOD_MMA(W, KP0) do { _Pragma("unroll") for (int kk = 0; kk < 32; ++kk) acc = __builtin_amdgcn_mfma_f32_32x32x2f32(ap[((KP0) + kk) * 64], W[kk], acc, 0, 0, 0); } while (0)
; #define MOD WSP(float, WS_MOD)
; __device__ __forceinline__ void p0_prologue(Frame& F) {
;     ...
;             MOD_MMA(wB, kp + 32);
;         }
;     ...
;         __syncthreads();
;         LAS float* RED = (LAS float*)(F.lds + RING_OFF) + s * 1024;
;         if (kh == 1) {
; #pragma unroll
;             for (int r = 0; r < 16; ++r) RED[r * 64 + lane] = acc[r]; }
;         __syncthreads();
;         if (kh == 0) { const float bm = b_mod[col];
; #pragma unroll
;             for (int r = 0; r < 16; ++r) { const int R = rt * 32 + (r & 3) + 8 * (r >> 2) + 4 * hi; if (R < 144) MOD[(size_t)R * NMOD + col] = acc[r] + RED[r * 64 + lane] + bm; } }
	v_mfma_f32_32x32x2_f32 v[2:17], v58, v66, v[2:17]
	v_mfma_f32_32x32x2_f32 v[2:17], v59, v67, v[2:17]
	v_mfma_f32_32x32x2_f32 v[2:17], v60, v68, v[2:17]
	v_mfma_f32_32x32x2_f32 v[2:17], v61, v69, v[2:17]
	v_mfma_f32_32x32x2_f32 v[2:17], v62, v70, v[2:17]
	v_mfma_f32_32x32x2_f32 v[2:17], v63, v71, v[2:17]
	v_mfma_f32_32x32x2_f32 v[2:17], v64, v72, v[2:17]
	v_mfma_f32_32x32x2_f32 v[2:17], v65, v73, v[2:17]
	ds_read2st64_b32 v[58:59], v28 offset0:40 offset1:41
	ds_read2st64_b32 v[60:61], v28 offset0:42 offset1:43
	ds_read2st64_b32 v[62:63], v28 offset0:44 offset1:45
	ds_read2st64_b32 v[64:65], v28 offset0:46 offset1:47
	s_waitcnt lgkmcnt(0)
	v_mfma_f32_32x32x2_f32 v[2:17], v58, v74, v[2:17]
	v_mfma_f32_32x32x2_f32 v[2:17], v59, v75, v[2:17]
	v_mfma_f32_32x32x2_f32 v[2:17], v60, v76, v[2:17]
	v_mfma_f32_32x32x2_f32 v[2:17], v61, v77, v[2:17]
	v_mfma_f32_32x32x2_f32 v[2:17], v62, v78, v[2:17]
	v_mfma_f32_32x32x2_f32 v[2:17], v63, v79, v[2:17]
	v_mfma_f32_32x32x2_f32 v[2:17], v64, v80, v[2:17]
	v_mfma_f32_32x32x2_f32 v[2:17], v65, v81, v[2:17]
	ds_read2st64_b32 v[58:59], v28 offset0:48 offset1:49
	ds_read2st64_b32 v[60:61], v28 offset0:50 offset1:51
	ds_read2st64_b32 v[62:63], v28 offset0:52 offset1:53
	ds_read2st64_b32 v[64:65], v28 offset0:54 offset1:55
	s_waitcnt lgkmcnt(0)
	v_mfma_f32_32x32x2_f32 v[2:17], v58, v82, v[2:17]
	v_mfma_f32_32x32x2_f32 v[2:17], v59, v83, v[2:17]
	v_mfma_f32_32x32x2_f32 v[2:17], v60, v84, v[2:17]
	v_mfma_f32_32x32x2_f32 v[2:17], v61, v85, v[2:17]
	v_mfma_f32_32x32x2_f32 v[2:17], v62, v86, v[2:17]
	v_mfma_f32_32x32x2_f32 v[2:17], v63, v87, v[2:17]
	v_mfma_f32_32x32x2_f32 v[2:17], v64, v88, v[2:17]
	v_mfma_f32_32x32x2_f32 v[2:17], v65, v89, v[2:17]
	ds_read2st64_b32 v[58:59], v28 offset0:56 offset1:57
	ds_read2st64_b32 v[60:61], v28 offset0:58 offset1:59
	ds_read2st64_b32 v[62:63], v28 offset0:60 offset1:61
	ds_read2st64_b32 v[64:65], v28 offset0:62 offset1:63
	v_add_u32_e32 v28, 0x4000, v28
	s_waitcnt lgkmcnt(0)
	v_mfma_f32_32x32x2_f32 v[2:17], v58, v90, v[2:17]
	v_mfma_f32_32x32x2_f32 v[2:17], v59, v91, v[2:17]
	v_mfma_f32_32x32x2_f32 v[2:17], v60, v92, v[2:17]
	v_mfma_f32_32x32x2_f32 v[2:17], v61, v93, v[2:17]
	v_mfma_f32_32x32x2_f32 v[2:17], v62, v94, v[2:17]
	v_mfma_f32_32x32x2_f32 v[2:17], v63, v95, v[2:17]
	v_mfma_f32_32x32x2_f32 v[2:17], v64, v96, v[2:17]
	v_mfma_f32_32x32x2_f32 v[2:17], v65, v97, v[2:17]
	s_cbranch_scc1 .LBB0_31
	s_lshl_b32 s4, s6, 12
	s_add_i32 s4, s4, 0
	s_cmp_lg_u32 s7, 1
	v_lshl_add_u32 v22, v1, 2, s4
	s_barrier
	s_cbranch_scc1 .LBB0_34
	s_nop 10
	ds_write2st64_b32 v22, v2, v3 offset1:1
	ds_write2st64_b32 v22, v4, v5 offset0:2 offset1:3
	ds_write2st64_b32 v22, v6, v7 offset0:4 offset1:5
	ds_write2st64_b32 v22, v8, v9 offset0:6 offset1:7
	ds_write2st64_b32 v22, v10, v11 offset0:8 offset1:9
	ds_write2st64_b32 v22, v12, v13 offset0:10 offset1:11
	ds_write2st64_b32 v22, v14, v15 offset0:12 offset1:13
	ds_write2st64_b32 v22, v16, v17 offset0:14 offset1:15
.LBB0_34:
	s_cmpk_gt_u32 s76, 0xff
	s_waitcnt vmcnt(0) lgkmcnt(0)
	s_barrier
	s_cbranch_scc1 .LBB0_68
	v_lshlrev_b64 v[20:21], 2, v[20:21]
	s_waitcnt vmcnt(0)
	v_lshl_add_u64 v[24:25], s[30:31], 0, v[20:21]
	global_load_dword v23, v[24:25], off
	s_lshl_b32 s3, s3, 5
	v_lshl_add_u32 v19, v19, 2, s3
	v_lshl_add_u64 v[20:21], s[10:11], 0, v[20:21]
	s_mov_b64 s[4:5], 0x1a00000
	s_movk_i32 s3, 0x90
	v_lshl_add_u64 v[20:21], v[20:21], 0, s[4:5]
	v_cmp_gt_i32_e32 vcc, s3, v19
	s_and_saveexec_b64 s[4:5], vcc
	s_cbranch_execz .LBB0_37
	ds_read_b32 v24, v22
	s_movk_i32 s6, 0x6000
	s_waitcnt lgkmcnt(0)
	v_add_f32_e32 v2, v2, v24
	s_waitcnt vmcnt(0)
	v_add_f32_e32 v2, v23, v2
	v_mad_i64_i32 v[24:25], s[6:7], v19, s6, v[20:21]
	global_store_dword v[24:25], v2, off
